# accumulator zeroing between GEMM1/GEMM3 units done with 64-bit moves (half the VALU instructions)
# speedup vs baseline: 1.0025x; 1.0025x over previous
; template <class Epi, class Sched, bool ALIGN_EPI = false, bool SP2 = false>
; __device__ __forceinline__ void gemm_phase(PG8_LAS unsigned char* lds, const Gemm g, const Sched& S, const Epi& E) {
;     ...
;         const bool has_next = S.next(ui + 1, nxt);
;         const char* nA = has_next ? (const char*)g.A + (size_t)nxt.pm * tstep + (size_t)nxt.kt0 * kstep : cA; const char* nB = has_next ? (const char*)g.Bt + (size_t)nxt.pn * tstep + (size_t)nxt.kt0 * kstep : cB;
;     ...
;         if (!has_next) break;
; #pragma unroll
;         for (int a = 0; a < 2; ++a)
; #pragma unroll
;             for (int b = 0; b < 2; ++b)
; #pragma unroll
;                 for (int m = 0; m < 4; ++m)
; #pragma unroll
;                     for (int n = 0; n < 2; ++n) acc[a][b][m][n] = (f32x4){0.f, 0.f, 0.f, 0.f};
;         cur = nxt; cA = nA; cB = nB; ++ui;
.LBB0_365:
	s_ashr_i32 s71, s70, 31
	s_lshl_b64 s[0:1], s[70:71], 21
	s_add_u32 s72, s53, s0
	s_addc_u32 s73, s55, s1
	s_and_b64 s[0:1], s[14:15], exec
	s_cselect_b32 s0, s73, s11
	s_cselect_b32 s1, s72, s10
	s_ashr_i32 s69, s68, 31
	s_lshl_b64 s[74:75], s[68:69], 21
	s_add_u32 s74, s57, s74
	s_addc_u32 s75, s65, s75
	s_and_b64 s[14:15], s[14:15], exec
	s_cselect_b32 s61, s75, s13
	s_cselect_b32 s69, s74, s12
	s_add_u32 s10, s10, 0x100080
	s_addc_u32 s11, s11, 0
	s_add_u32 s71, s12, 0x100
	v_mov_b32_e32 v2, 0
	s_addc_u32 s77, s13, 0
	s_mov_b32 s80, -2
	v_mov_b32_e32 v3, 0
	v_mov_b64_e32 v[4:5], 0
	v_mov_b64_e32 v[6:7], 0
	v_mov_b64_e32 v[8:9], 0
	v_mov_b64_e32 v[18:19], 0
	v_mov_b64_e32 v[20:21], 0
	v_mov_b64_e32 v[22:23], 0
	v_mov_b64_e32 v[24:25], 0
	v_mov_b64_e32 v[34:35], 0
	v_mov_b64_e32 v[36:37], 0
	v_mov_b64_e32 v[38:39], 0
	v_mov_b64_e32 v[40:41], 0
	v_mov_b64_e32 v[50:51], 0
	v_mov_b64_e32 v[52:53], 0
	v_mov_b64_e32 v[54:55], 0
	v_mov_b64_e32 v[56:57], 0
	v_mov_b64_e32 v[10:11], 0
	v_mov_b64_e32 v[12:13], 0
	v_mov_b64_e32 v[14:15], 0
	v_mov_b64_e32 v[16:17], 0
	v_mov_b64_e32 v[26:27], 0
	v_mov_b64_e32 v[28:29], 0
	v_mov_b64_e32 v[30:31], 0
	v_mov_b64_e32 v[32:33], 0
	v_mov_b64_e32 v[42:43], 0
	v_mov_b64_e32 v[44:45], 0
	v_mov_b64_e32 v[46:47], 0
	v_mov_b64_e32 v[48:49], 0
	v_mov_b64_e32 v[58:59], 0
	v_mov_b64_e32 v[60:61], 0
	v_mov_b64_e32 v[62:63], 0
	v_mov_b64_e32 v[64:65], 0
	v_mov_b64_e32 v[66:67], 0
	v_mov_b64_e32 v[68:69], 0
	v_mov_b64_e32 v[70:71], 0
	v_mov_b64_e32 v[72:73], 0
	v_mov_b64_e32 v[82:83], 0
	v_mov_b64_e32 v[84:85], 0
	v_mov_b64_e32 v[86:87], 0
	v_mov_b64_e32 v[88:89], 0
	v_mov_b64_e32 v[98:99], 0
	v_mov_b64_e32 v[100:101], 0
	v_mov_b64_e32 v[102:103], 0
	v_mov_b64_e32 v[104:105], 0
	v_mov_b64_e32 v[114:115], 0
	v_mov_b64_e32 v[116:117], 0
	v_mov_b64_e32 v[118:119], 0
	v_mov_b64_e32 v[120:121], 0
	v_mov_b64_e32 v[74:75], 0
	v_mov_b64_e32 v[76:77], 0
	v_mov_b64_e32 v[78:79], 0
	v_mov_b64_e32 v[80:81], 0
	v_mov_b64_e32 v[90:91], 0
	v_mov_b64_e32 v[92:93], 0
	v_mov_b64_e32 v[94:95], 0
	v_mov_b64_e32 v[96:97], 0
	v_mov_b64_e32 v[106:107], 0
	v_mov_b64_e32 v[108:109], 0
	v_mov_b64_e32 v[110:111], 0
	v_mov_b64_e32 v[112:113], 0
	v_mov_b64_e32 v[122:123], 0
	v_mov_b64_e32 v[124:125], 0
	v_mov_b64_e32 v[126:127], 0
	v_mov_b64_e32 v[128:129], 0
	s_waitcnt vmcnt(0)

; template <class Epi, class Sched, bool ALIGN_EPI = false, bool SP2 = false>
; __device__ __forceinline__ void gemm_phase(PG8_LAS unsigned char* lds, const Gemm g, const Sched& S, const Epi& E) {
;     ...
;         const bool has_next = S.next(ui + 1, nxt);
;         const char* nA = has_next ? (const char*)g.A + (size_t)nxt.pm * tstep + (size_t)nxt.kt0 * kstep : cA; const char* nB = has_next ? (const char*)g.Bt + (size_t)nxt.pn * tstep + (size_t)nxt.kt0 * kstep : cB;
;     ...
;         if (!has_next) break;
; #pragma unroll
;         for (int a = 0; a < 2; ++a)
; #pragma unroll
;             for (int b = 0; b < 2; ++b)
; #pragma unroll
;                 for (int m = 0; m < 4; ++m)
; #pragma unroll
;                     for (int n = 0; n < 2; ++n) acc[a][b][m][n] = (f32x4){0.f, 0.f, 0.f, 0.f};
;         cur = nxt; cA = nA; cB = nB; ++ui;
.LBB0_2649:
	s_ashr_i32 s79, s78, 31
	s_lshl_b64 s[80:81], s[78:79], 21
	s_add_u32 s80, s57, s80
	s_addc_u32 s81, s60, s81
	s_and_b64 s[82:83], s[16:17], exec
	s_cselect_b32 s19, s81, s87
	s_cselect_b32 s69, s80, s86
	s_ashr_i32 s77, s76, 31
	s_lshl_b64 s[82:83], s[76:77], 21
	s_add_u32 s82, s30, s82
	s_addc_u32 s83, s31, s83
	s_and_b64 s[90:91], s[16:17], exec
	s_cselect_b32 s77, s83, s89
	s_cselect_b32 s79, s82, s88
	s_add_u32 s86, s86, 0x100080
	s_addc_u32 s87, s87, 0
	s_add_u32 s85, s88, 0x100
	v_mov_b32_e32 v18, 0
	s_addc_u32 s92, s89, 0
	s_mov_b32 s93, -2
	v_mov_b32_e32 v19, 0
	v_mov_b64_e32 v[20:21], 0
	v_mov_b64_e32 v[22:23], 0
	v_mov_b64_e32 v[24:25], 0
	v_mov_b64_e32 v[34:35], 0
	v_mov_b64_e32 v[36:37], 0
	v_mov_b64_e32 v[38:39], 0
	v_mov_b64_e32 v[40:41], 0
	v_mov_b64_e32 v[82:83], 0
	v_mov_b64_e32 v[84:85], 0
	v_mov_b64_e32 v[86:87], 0
	v_mov_b64_e32 v[88:89], 0
	v_mov_b64_e32 v[98:99], 0
	v_mov_b64_e32 v[100:101], 0
	v_mov_b64_e32 v[102:103], 0
	v_mov_b64_e32 v[104:105], 0
	v_mov_b64_e32 v[26:27], 0
	v_mov_b64_e32 v[28:29], 0
	v_mov_b64_e32 v[30:31], 0
	v_mov_b64_e32 v[32:33], 0
	v_mov_b64_e32 v[74:75], 0
	v_mov_b64_e32 v[76:77], 0
	v_mov_b64_e32 v[78:79], 0
	v_mov_b64_e32 v[80:81], 0
	v_mov_b64_e32 v[90:91], 0
	v_mov_b64_e32 v[92:93], 0
	v_mov_b64_e32 v[94:95], 0
	v_mov_b64_e32 v[96:97], 0
	v_mov_b64_e32 v[106:107], 0
	v_mov_b64_e32 v[108:109], 0
	v_mov_b64_e32 v[110:111], 0
	v_mov_b64_e32 v[112:113], 0
	v_mov_b64_e32 v[114:115], 0
	v_mov_b64_e32 v[116:117], 0
	v_mov_b64_e32 v[118:119], 0
	v_mov_b64_e32 v[120:121], 0
	v_mov_b64_e32 v[130:131], 0
	v_mov_b64_e32 v[132:133], 0
	v_mov_b64_e32 v[134:135], 0
	v_mov_b64_e32 v[136:137], 0
	v_mov_b64_e32 v[146:147], 0
	v_mov_b64_e32 v[148:149], 0
	v_mov_b64_e32 v[150:151], 0
	v_mov_b64_e32 v[152:153], 0
	v_mov_b64_e32 v[162:163], 0
	v_mov_b64_e32 v[164:165], 0
	v_mov_b64_e32 v[166:167], 0
	v_mov_b64_e32 v[168:169], 0
	v_mov_b64_e32 v[122:123], 0
	v_mov_b64_e32 v[124:125], 0
	v_mov_b64_e32 v[126:127], 0
	v_mov_b64_e32 v[128:129], 0
	v_mov_b64_e32 v[138:139], 0
	v_mov_b64_e32 v[140:141], 0
	v_mov_b64_e32 v[142:143], 0
	v_mov_b64_e32 v[144:145], 0
	v_mov_b64_e32 v[154:155], 0
	v_mov_b64_e32 v[156:157], 0
	v_mov_b64_e32 v[158:159], 0
	v_mov_b64_e32 v[160:161], 0
	v_mov_b64_e32 v[2:3], 0
	v_mov_b64_e32 v[4:5], 0
	v_mov_b64_e32 v[6:7], 0
	v_mov_b64_e32 v[8:9], 0
